# mixer phase chunks dealt round-robin over the XCDs (consecutive 128-token chunks on different XCDs) on top of the attention remap
# baseline (speedup 1.0000x reference)
; __device__ __forceinline__ void mixer_phase(LAS unsigned char* lds, const bf16_t* U, const bf16_t* Gt, const bf16_t* UZ, const bf16_t* V, const float* conv_w, const float* sg_norm,
;                                             const bf16_t* WTR, const float* sg_b, bf16_t* Y, int vcu, int G) {
;     ...
;     for (int unit = vcu; unit < BATCH * 64 * 8; unit += G) {
;         const int g = unit & 7, cch = (unit >> 3) & 63, b = unit >> 9; const size_t r0 = (size_t)b * SEQ + cch * 128;
;         const int ch = 128 * g + 8 * c8; const size_t row = r0 + 4 * rg;
;         u32x4 ur[6], gv[4], vv[4], uz[4];
;         const bool halo0 = (cch == 0 && rg == 0);
; #pragma unroll
;         for (int i = 0; i < 4; ++i) vv[i] = *(const u32x4*)(V + (r0 + s) * D + 128 * g + 32 * qd + 8 * i);
; #pragma unroll
;         for (int i = 0; i < 6; ++i) { if (i < 2 && halo0) ur[i] = (u32x4){0u, 0u, 0u, 0u}; else ur[i] = *(const u32x4*)(U + (row + i - 2) * D + ch); }
.LBB0_283:
	s_and_b32 s100, s36, 0x307
	s_bfe_u32 s101, s36, 0x20003
	s_lshl_b32 s101, s101, 6
	s_or_b32 s100, s100, s101
	s_bfe_u32 s101, s36, 0x30005
	s_lshl_b32 s101, s101, 3
	s_or_b32 s100, s100, s101
	s_ashr_i32 s24, s100, 9
	s_bfe_u32 s30, s100, 0x60003
	s_ashr_i32 s25, s24, 31
	s_lshl_b64 s[26:27], s[24:25], 13
	s_lshl_b32 s14, s30, 7
	s_or_b32 s26, s26, s14
	v_mov_b32_e32 v99, s27
	v_or_b32_e32 v98, s26, v82
	s_and_b32 s40, s100, 7
	v_lshlrev_b64 v[2:3], 11, v[98:99]
	v_lshl_add_u64 v[4:5], s[64:65], 0, v[2:3]
	s_lshl_b32 s14, s40, 8
	v_lshl_add_u64 v[4:5], v[4:5], 0, s[14:15]
	v_lshl_add_u64 v[4:5], v[4:5], 0, v[96:97]
	global_load_dwordx4 v[58:61], v[4:5], off offset:48
	global_load_dwordx4 v[62:65], v[4:5], off offset:32
	global_load_dwordx4 v[66:69], v[4:5], off offset:16
	global_load_dwordx4 v[70:73], v[4:5], off
	s_lshl_b32 s37, s40, 7
	s_cmp_lg_u32 s30, 0
	v_or_b32_e32 v74, s37, v83
	v_mov_b32_e32 v103, s27
	v_or_b32_e32 v102, s26, v84
	s_cselect_b64 s[26:27], -1, 0
	s_or_b64 s[26:27], s[26:27], s[0:1]
	v_lshlrev_b64 v[4:5], 11, v[102:103]
	v_lshlrev_b32_e32 v86, 1, v74
	v_mov_b32_e32 v34, 0
	v_mov_b32_e32 v35, 0
	v_mov_b32_e32 v36, 0
	v_mov_b32_e32 v37, 0
	s_and_saveexec_b64 s[30:31], s[26:27]
	s_cbranch_execz .LBB0_285
	v_lshlrev_b64 v[6:7], 11, v[102:103]
	v_lshl_add_u64 v[6:7], s[60:61], 0, v[6:7]
	v_lshl_add_u64 v[6:7], v[6:7], 0, v[86:87]
	global_load_dwordx4 v[34:37], v[6:7], off offset:-4096
